# v6: v5 plus accumulator zeroing with 64 v_mov_b64 instead of 128 v_mov_b32 per tile in all GEMM tile loops
# speedup vs baseline: 1.0141x; 1.0036x over previous
; template <class Epi, class Sched, bool ALIGN_EPI = false, bool SP2 = false>
; __device__ __forceinline__ void gemm_phase(PG8_LAS unsigned char* lds, const Gemm g, const Sched& S, const Epi& E, const int wid) {
;     ...
;         const bool has_next = S.next(ui + 1, nxt);
;         const char* nA = has_next ? (const char*)g.A + (size_t)nxt.pm * tstep : cA; const char* nB = has_next ? (const char*)g.Bt + (size_t)nxt.pn * tstep : cB;
;     ...
;         for (int a = 0; a < 2; ++a)
; #pragma unroll
;             for (int b = 0; b < 2; ++b)
; #pragma unroll
;                 for (int m = 0; m < 4; ++m)
; #pragma unroll
;                     for (int n = 0; n < 2; ++n) acc[a][b][m][n] = (f32x4){zf_, zf_, zf_, zf_};
.LBB0_187:
	s_ashr_i32 s19, s18, 31
	s_lshl_b64 s[22:23], s[18:19], 17
	s_add_u32 s22, s52, s22
	s_addc_u32 s23, s64, s23
	s_and_b64 s[26:27], s[6:7], exec
	s_cselect_b32 s19, s23, s29
	s_cselect_b32 s93, s22, s28
	s_ashr_i32 s17, s16, 31
	s_lshl_b64 s[26:27], s[16:17], 17
	s_add_u32 s26, s65, s26
	s_addc_u32 s27, s66, s27
	s_and_b64 s[30:31], s[6:7], exec
	s_cselect_b32 s17, s27, s25
	s_cselect_b32 s94, s26, s24
	s_mov_b32 s36, 0
	s_mov_b64 s[30:31], -1
	s_mov_b64 s[34:35], 0
	v_mov_b64_e32 v[2:3], 0
	v_mov_b64_e32 v[4:5], 0
	v_mov_b64_e32 v[6:7], 0
	v_mov_b64_e32 v[8:9], 0
	v_mov_b64_e32 v[10:11], 0
	v_mov_b64_e32 v[12:13], 0
	v_mov_b64_e32 v[14:15], 0
	v_mov_b64_e32 v[16:17], 0
	v_mov_b64_e32 v[18:19], 0
	v_mov_b64_e32 v[20:21], 0
	v_mov_b64_e32 v[22:23], 0
	v_mov_b64_e32 v[24:25], 0
	v_mov_b64_e32 v[26:27], 0
	v_mov_b64_e32 v[28:29], 0
	v_mov_b64_e32 v[30:31], 0
	v_mov_b64_e32 v[32:33], 0
	v_mov_b64_e32 v[34:35], 0
	v_mov_b64_e32 v[36:37], 0
	v_mov_b64_e32 v[38:39], 0
	v_mov_b64_e32 v[40:41], 0
	v_mov_b64_e32 v[42:43], 0
	v_mov_b64_e32 v[44:45], 0
	v_mov_b64_e32 v[46:47], 0
	v_mov_b64_e32 v[48:49], 0
	v_mov_b64_e32 v[50:51], 0
	v_mov_b64_e32 v[52:53], 0
	v_mov_b64_e32 v[54:55], 0
	v_mov_b64_e32 v[56:57], 0
	v_mov_b64_e32 v[58:59], 0
	v_mov_b64_e32 v[60:61], 0
	v_mov_b64_e32 v[62:63], 0
	v_mov_b64_e32 v[64:65], 0
	v_mov_b64_e32 v[66:67], 0
	v_mov_b64_e32 v[68:69], 0
	v_mov_b64_e32 v[70:71], 0
	v_mov_b64_e32 v[72:73], 0
	v_mov_b64_e32 v[74:75], 0
	v_mov_b64_e32 v[76:77], 0
	v_mov_b64_e32 v[78:79], 0
	v_mov_b64_e32 v[80:81], 0
	v_mov_b64_e32 v[82:83], 0
	v_mov_b64_e32 v[84:85], 0
	v_mov_b64_e32 v[86:87], 0
	v_mov_b64_e32 v[88:89], 0
	v_mov_b64_e32 v[90:91], 0
	v_mov_b64_e32 v[92:93], 0
	v_mov_b64_e32 v[94:95], 0
	v_mov_b64_e32 v[96:97], 0
	v_mov_b64_e32 v[98:99], 0
	v_mov_b64_e32 v[100:101], 0
	v_mov_b64_e32 v[102:103], 0
	v_mov_b64_e32 v[104:105], 0
	v_mov_b64_e32 v[106:107], 0
	v_mov_b64_e32 v[108:109], 0
	v_mov_b64_e32 v[110:111], 0
	v_mov_b64_e32 v[112:113], 0
	v_mov_b64_e32 v[114:115], 0
	v_mov_b64_e32 v[116:117], 0
	v_mov_b64_e32 v[118:119], 0
	v_mov_b64_e32 v[120:121], 0
	v_mov_b64_e32 v[122:123], 0
	v_mov_b64_e32 v[124:125], 0
	v_mov_b64_e32 v[126:127], 0
	v_mov_b64_e32 v[128:129], 0

; template <class Epi, class Sched, bool ALIGN_EPI = false, bool SP2 = false>
; __device__ __forceinline__ void gemm_phase(PG8_LAS unsigned char* lds, const Gemm g, const Sched& S, const Epi& E, const int wid) {
;     ...
;         const bool has_next = S.next(ui + 1, nxt);
;         const char* nA = has_next ? (const char*)g.A + (size_t)nxt.pm * tstep : cA; const char* nB = has_next ? (const char*)g.Bt + (size_t)nxt.pn * tstep : cB;
;     ...
;         for (int a = 0; a < 2; ++a)
; #pragma unroll
;             for (int b = 0; b < 2; ++b)
; #pragma unroll
;                 for (int m = 0; m < 4; ++m)
; #pragma unroll
;                     for (int n = 0; n < 2; ++n) acc[a][b][m][n] = (f32x4){zf_, zf_, zf_, zf_};
.LBB0_213:
	s_ashr_i32 s27, s26, 31
	s_lshl_b64 s[28:29], s[26:27], 20
	s_add_u32 s28, s10, s28
	s_addc_u32 s29, s11, s29
	s_and_b64 s[30:31], s[6:7], exec
	s_cselect_b32 s3, s29, s39
	s_cselect_b32 s23, s28, s38
	s_ashr_i32 s25, s24, 31
	s_lshl_b64 s[30:31], s[24:25], 20
	s_add_u32 s30, s44, s30
	s_addc_u32 s31, s45, s31
	s_and_b64 s[42:43], s[6:7], exec
	s_cselect_b32 s25, s31, s41
	s_cselect_b32 s27, s30, s40
	s_add_u32 s38, s38, 0x80080
	s_addc_u32 s39, s39, 0
	s_add_u32 s35, s40, 0x100
	s_addc_u32 s37, s41, 0
	s_mov_b32 s46, -2
	v_mov_b64_e32 v[2:3], 0
	v_mov_b64_e32 v[4:5], 0
	v_mov_b64_e32 v[6:7], 0
	v_mov_b64_e32 v[8:9], 0
	v_mov_b64_e32 v[10:11], 0
	v_mov_b64_e32 v[12:13], 0
	v_mov_b64_e32 v[14:15], 0
	v_mov_b64_e32 v[16:17], 0
	v_mov_b64_e32 v[18:19], 0
	v_mov_b64_e32 v[20:21], 0
	v_mov_b64_e32 v[22:23], 0
	v_mov_b64_e32 v[24:25], 0
	v_mov_b64_e32 v[26:27], 0
	v_mov_b64_e32 v[28:29], 0
	v_mov_b64_e32 v[30:31], 0
	v_mov_b64_e32 v[32:33], 0
	v_mov_b64_e32 v[34:35], 0
	v_mov_b64_e32 v[36:37], 0
	v_mov_b64_e32 v[38:39], 0
	v_mov_b64_e32 v[40:41], 0
	v_mov_b64_e32 v[42:43], 0
	v_mov_b64_e32 v[44:45], 0
	v_mov_b64_e32 v[46:47], 0
	v_mov_b64_e32 v[48:49], 0
	v_mov_b64_e32 v[50:51], 0
	v_mov_b64_e32 v[52:53], 0
	v_mov_b64_e32 v[54:55], 0
	v_mov_b64_e32 v[56:57], 0
	v_mov_b64_e32 v[58:59], 0
	v_mov_b64_e32 v[60:61], 0
	v_mov_b64_e32 v[62:63], 0
	v_mov_b64_e32 v[64:65], 0
	v_mov_b64_e32 v[66:67], 0
	v_mov_b64_e32 v[68:69], 0
	v_mov_b64_e32 v[70:71], 0
	v_mov_b64_e32 v[72:73], 0
	v_mov_b64_e32 v[74:75], 0
	v_mov_b64_e32 v[76:77], 0
	v_mov_b64_e32 v[78:79], 0
	v_mov_b64_e32 v[80:81], 0
	v_mov_b64_e32 v[82:83], 0
	v_mov_b64_e32 v[84:85], 0
	v_mov_b64_e32 v[86:87], 0
	v_mov_b64_e32 v[88:89], 0
	v_mov_b64_e32 v[90:91], 0
	v_mov_b64_e32 v[92:93], 0
	v_mov_b64_e32 v[94:95], 0
	v_mov_b64_e32 v[96:97], 0
	v_mov_b64_e32 v[98:99], 0
	v_mov_b64_e32 v[100:101], 0
	v_mov_b64_e32 v[102:103], 0
	v_mov_b64_e32 v[104:105], 0
	v_mov_b64_e32 v[106:107], 0
	v_mov_b64_e32 v[108:109], 0
	v_mov_b64_e32 v[110:111], 0
	v_mov_b64_e32 v[112:113], 0
	v_mov_b64_e32 v[114:115], 0
	v_mov_b64_e32 v[116:117], 0
	v_mov_b64_e32 v[118:119], 0
	v_mov_b64_e32 v[120:121], 0
	v_mov_b64_e32 v[122:123], 0
	v_mov_b64_e32 v[124:125], 0
	v_mov_b64_e32 v[126:127], 0
	v_mov_b64_e32 v[128:129], 0

; template <class Epi, class Sched, bool ALIGN_EPI = false, bool SP2 = false>
; __device__ __forceinline__ void gemm_phase(PG8_LAS unsigned char* lds, const Gemm g, const Sched& S, const Epi& E, const int wid) {
;     ...
;         const bool has_next = S.next(ui + 1, nxt);
;         const char* nA = has_next ? (const char*)g.A + (size_t)nxt.pm * tstep : cA; const char* nB = has_next ? (const char*)g.Bt + (size_t)nxt.pn * tstep : cB;
;     ...
;         for (int a = 0; a < 2; ++a)
; #pragma unroll
;             for (int b = 0; b < 2; ++b)
; #pragma unroll
;                 for (int m = 0; m < 4; ++m)
; #pragma unroll
;                     for (int n = 0; n < 2; ++n) acc[a][b][m][n] = (f32x4){zf_, zf_, zf_, zf_};
.LBB0_341:
	s_ashr_i32 s23, s22, 31
	s_lshl_b64 s[24:25], s[22:23], 20
	s_add_u32 s24, s38, s24
	s_addc_u32 s25, s39, s25
	s_and_b64 s[26:27], s[6:7], exec
	s_cselect_b32 s23, s25, s31
	s_cselect_b32 s29, s24, s30
	s_ashr_i32 s21, s20, 31
	s_lshl_b64 s[26:27], s[20:21], 20
	s_add_u32 s26, s55, s26
	s_addc_u32 s27, s64, s27
	s_and_b64 s[36:37], s[6:7], exec
	s_cselect_b32 s21, s27, s35
	s_cselect_b32 s88, s26, s34
	s_add_u32 s30, s30, 0x80080
	s_addc_u32 s31, s31, 0
	s_add_u32 s89, s34, 0x100
	s_addc_u32 s90, s35, 0
	s_mov_b32 s91, -2
	v_mov_b64_e32 v[2:3], 0
	v_mov_b64_e32 v[4:5], 0
	v_mov_b64_e32 v[6:7], 0
	v_mov_b64_e32 v[8:9], 0
	v_mov_b64_e32 v[10:11], 0
	v_mov_b64_e32 v[12:13], 0
	v_mov_b64_e32 v[14:15], 0
	v_mov_b64_e32 v[16:17], 0
	v_mov_b64_e32 v[18:19], 0
	v_mov_b64_e32 v[20:21], 0
	v_mov_b64_e32 v[22:23], 0
	v_mov_b64_e32 v[24:25], 0
	v_mov_b64_e32 v[26:27], 0
	v_mov_b64_e32 v[28:29], 0
	v_mov_b64_e32 v[30:31], 0
	v_mov_b64_e32 v[32:33], 0
	v_mov_b64_e32 v[34:35], 0
	v_mov_b64_e32 v[36:37], 0
	v_mov_b64_e32 v[38:39], 0
	v_mov_b64_e32 v[40:41], 0
	v_mov_b64_e32 v[42:43], 0
	v_mov_b64_e32 v[44:45], 0
	v_mov_b64_e32 v[46:47], 0
	v_mov_b64_e32 v[48:49], 0
	v_mov_b64_e32 v[50:51], 0
	v_mov_b64_e32 v[52:53], 0
	v_mov_b64_e32 v[54:55], 0
	v_mov_b64_e32 v[56:57], 0
	v_mov_b64_e32 v[58:59], 0
	v_mov_b64_e32 v[60:61], 0
	v_mov_b64_e32 v[62:63], 0
	v_mov_b64_e32 v[64:65], 0
	v_mov_b64_e32 v[66:67], 0
	v_mov_b64_e32 v[68:69], 0
	v_mov_b64_e32 v[70:71], 0
	v_mov_b64_e32 v[72:73], 0
	v_mov_b64_e32 v[74:75], 0
	v_mov_b64_e32 v[76:77], 0
	v_mov_b64_e32 v[78:79], 0
	v_mov_b64_e32 v[80:81], 0
	v_mov_b64_e32 v[82:83], 0
	v_mov_b64_e32 v[84:85], 0
	v_mov_b64_e32 v[86:87], 0
	v_mov_b64_e32 v[88:89], 0
	v_mov_b64_e32 v[90:91], 0
	v_mov_b64_e32 v[92:93], 0
	v_mov_b64_e32 v[94:95], 0
	v_mov_b64_e32 v[96:97], 0
	v_mov_b64_e32 v[98:99], 0
	v_mov_b64_e32 v[100:101], 0
	v_mov_b64_e32 v[102:103], 0
	v_mov_b64_e32 v[104:105], 0
	v_mov_b64_e32 v[106:107], 0
	v_mov_b64_e32 v[108:109], 0
	v_mov_b64_e32 v[110:111], 0
	v_mov_b64_e32 v[112:113], 0
	v_mov_b64_e32 v[114:115], 0
	v_mov_b64_e32 v[116:117], 0
	v_mov_b64_e32 v[118:119], 0
	v_mov_b64_e32 v[120:121], 0
	v_mov_b64_e32 v[122:123], 0
	v_mov_b64_e32 v[124:125], 0
	v_mov_b64_e32 v[126:127], 0
	v_mov_b64_e32 v[128:129], 0

; template <class Epi, class Sched, bool ALIGN_EPI = false, bool SP2 = false>
; __device__ __forceinline__ void gemm_phase(PG8_LAS unsigned char* lds, const Gemm g, const Sched& S, const Epi& E, const int wid) {
;     ...
;         const bool has_next = S.next(ui + 1, nxt);
;         const char* nA = has_next ? (const char*)g.A + (size_t)nxt.pm * tstep : cA; const char* nB = has_next ? (const char*)g.Bt + (size_t)nxt.pn * tstep : cB;
;     ...
;         for (int a = 0; a < 2; ++a)
; #pragma unroll
;             for (int b = 0; b < 2; ++b)
; #pragma unroll
;                 for (int m = 0; m < 4; ++m)
; #pragma unroll
;                     for (int n = 0; n < 2; ++n) acc[a][b][m][n] = (f32x4){zf_, zf_, zf_, zf_};
.LBB0_374:
	s_ashr_i32 s23, s22, 31
	s_lshl_b64 s[24:25], s[22:23], 20
	s_add_u32 s24, s64, s24
	s_addc_u32 s25, s65, s25
	s_and_b64 s[26:27], s[6:7], exec
	s_cselect_b32 s23, s25, s31
	s_cselect_b32 s50, s24, s30
	s_ashr_i32 s21, s20, 31
	s_lshl_b64 s[26:27], s[20:21], 20
	s_add_u32 s26, s38, s26
	s_addc_u32 s27, s39, s27
	s_and_b64 s[36:37], s[6:7], exec
	s_cselect_b32 s21, s27, s35
	s_cselect_b32 s85, s26, s34
	s_add_u32 s30, s30, 0x80080
	s_addc_u32 s31, s31, 0
	s_add_u32 s86, s34, 0x100
	s_addc_u32 s87, s35, 0
	s_mov_b32 s88, -2
	v_mov_b64_e32 v[2:3], 0
	v_mov_b64_e32 v[4:5], 0
	v_mov_b64_e32 v[6:7], 0
	v_mov_b64_e32 v[8:9], 0
	v_mov_b64_e32 v[10:11], 0
	v_mov_b64_e32 v[12:13], 0
	v_mov_b64_e32 v[14:15], 0
	v_mov_b64_e32 v[16:17], 0
	v_mov_b64_e32 v[18:19], 0
	v_mov_b64_e32 v[20:21], 0
	v_mov_b64_e32 v[22:23], 0
	v_mov_b64_e32 v[24:25], 0
	v_mov_b64_e32 v[26:27], 0
	v_mov_b64_e32 v[28:29], 0
	v_mov_b64_e32 v[30:31], 0
	v_mov_b64_e32 v[32:33], 0
	v_mov_b64_e32 v[34:35], 0
	v_mov_b64_e32 v[36:37], 0
	v_mov_b64_e32 v[38:39], 0
	v_mov_b64_e32 v[40:41], 0
	v_mov_b64_e32 v[42:43], 0
	v_mov_b64_e32 v[44:45], 0
	v_mov_b64_e32 v[46:47], 0
	v_mov_b64_e32 v[48:49], 0
	v_mov_b64_e32 v[50:51], 0
	v_mov_b64_e32 v[52:53], 0
	v_mov_b64_e32 v[54:55], 0
	v_mov_b64_e32 v[56:57], 0
	v_mov_b64_e32 v[58:59], 0
	v_mov_b64_e32 v[60:61], 0
	v_mov_b64_e32 v[62:63], 0
	v_mov_b64_e32 v[64:65], 0
	v_mov_b64_e32 v[66:67], 0
	v_mov_b64_e32 v[68:69], 0
	v_mov_b64_e32 v[70:71], 0
	v_mov_b64_e32 v[72:73], 0
	v_mov_b64_e32 v[74:75], 0
	v_mov_b64_e32 v[76:77], 0
	v_mov_b64_e32 v[78:79], 0
	v_mov_b64_e32 v[80:81], 0
	v_mov_b64_e32 v[82:83], 0
	v_mov_b64_e32 v[84:85], 0
	v_mov_b64_e32 v[86:87], 0
	v_mov_b64_e32 v[88:89], 0
	v_mov_b64_e32 v[90:91], 0
	v_mov_b64_e32 v[92:93], 0
	v_mov_b64_e32 v[94:95], 0
	v_mov_b64_e32 v[96:97], 0
	v_mov_b64_e32 v[98:99], 0
	v_mov_b64_e32 v[100:101], 0
	v_mov_b64_e32 v[102:103], 0
	v_mov_b64_e32 v[104:105], 0
	v_mov_b64_e32 v[106:107], 0
	v_mov_b64_e32 v[108:109], 0
	v_mov_b64_e32 v[110:111], 0
	v_mov_b64_e32 v[112:113], 0
	v_mov_b64_e32 v[114:115], 0
	v_mov_b64_e32 v[116:117], 0
	v_mov_b64_e32 v[118:119], 0
	v_mov_b64_e32 v[120:121], 0
	v_mov_b64_e32 v[122:123], 0
	v_mov_b64_e32 v[124:125], 0
	v_mov_b64_e32 v[126:127], 0
	v_mov_b64_e32 v[128:129], 0

; template <class Epi, class Sched, bool ALIGN_EPI = false, bool SP2 = false>
; __device__ __forceinline__ void gemm_phase(PG8_LAS unsigned char* lds, const Gemm g, const Sched& S, const Epi& E, const int wid) {
;     ...
;         const bool has_next = S.next(ui + 1, nxt);
;         const char* nA = has_next ? (const char*)g.A + (size_t)nxt.pm * tstep : cA; const char* nB = has_next ? (const char*)g.Bt + (size_t)nxt.pn * tstep : cB;
;     ...
;         for (int a = 0; a < 2; ++a)
; #pragma unroll
;             for (int b = 0; b < 2; ++b)
; #pragma unroll
;                 for (int m = 0; m < 4; ++m)
; #pragma unroll
;                     for (int n = 0; n < 2; ++n) acc[a][b][m][n] = (f32x4){zf_, zf_, zf_, zf_};
.LBB0_404:
	s_ashr_i32 s19, s18, 31
	s_lshl_b64 s[20:21], s[18:19], 18
	s_add_u32 s20, s3, s20
	s_addc_u32 s21, s30, s21
	s_and_b64 s[22:23], s[6:7], exec
	s_cselect_b32 s19, s21, s25
	s_cselect_b32 s64, s20, s24
	s_ashr_i32 s17, s16, 31
	s_lshl_b64 s[22:23], s[16:17], 18
	s_add_u32 s22, s31, s22
	s_addc_u32 s23, s34, s23
	s_and_b64 s[28:29], s[6:7], exec
	s_cselect_b32 s17, s23, s27
	s_cselect_b32 s65, s22, s26
	s_add_u32 s24, s24, 0x20080
	s_addc_u32 s25, s25, 0
	s_add_u32 s66, s26, 0x100
	s_addc_u32 s67, s27, 0
	s_mov_b32 s84, -2
	v_mov_b64_e32 v[2:3], 0
	v_mov_b64_e32 v[4:5], 0
	v_mov_b64_e32 v[6:7], 0
	v_mov_b64_e32 v[8:9], 0
	v_mov_b64_e32 v[10:11], 0
	v_mov_b64_e32 v[12:13], 0
	v_mov_b64_e32 v[14:15], 0
	v_mov_b64_e32 v[16:17], 0
	v_mov_b64_e32 v[18:19], 0
	v_mov_b64_e32 v[20:21], 0
	v_mov_b64_e32 v[22:23], 0
	v_mov_b64_e32 v[24:25], 0
	v_mov_b64_e32 v[26:27], 0
	v_mov_b64_e32 v[28:29], 0
	v_mov_b64_e32 v[30:31], 0
	v_mov_b64_e32 v[32:33], 0
	v_mov_b64_e32 v[34:35], 0
	v_mov_b64_e32 v[36:37], 0
	v_mov_b64_e32 v[38:39], 0
	v_mov_b64_e32 v[40:41], 0
	v_mov_b64_e32 v[42:43], 0
	v_mov_b64_e32 v[44:45], 0
	v_mov_b64_e32 v[46:47], 0
	v_mov_b64_e32 v[48:49], 0
	v_mov_b64_e32 v[50:51], 0
	v_mov_b64_e32 v[52:53], 0
	v_mov_b64_e32 v[54:55], 0
	v_mov_b64_e32 v[56:57], 0
	v_mov_b64_e32 v[58:59], 0
	v_mov_b64_e32 v[60:61], 0
	v_mov_b64_e32 v[62:63], 0
	v_mov_b64_e32 v[64:65], 0
	v_mov_b64_e32 v[66:67], 0
	v_mov_b64_e32 v[68:69], 0
	v_mov_b64_e32 v[70:71], 0
	v_mov_b64_e32 v[72:73], 0
	v_mov_b64_e32 v[74:75], 0
	v_mov_b64_e32 v[76:77], 0
	v_mov_b64_e32 v[78:79], 0
	v_mov_b64_e32 v[80:81], 0
	v_mov_b64_e32 v[82:83], 0
	v_mov_b64_e32 v[84:85], 0
	v_mov_b64_e32 v[86:87], 0
	v_mov_b64_e32 v[88:89], 0
	v_mov_b64_e32 v[90:91], 0
	v_mov_b64_e32 v[92:93], 0
	v_mov_b64_e32 v[94:95], 0
	v_mov_b64_e32 v[96:97], 0
	v_mov_b64_e32 v[98:99], 0
	v_mov_b64_e32 v[100:101], 0
	v_mov_b64_e32 v[102:103], 0
	v_mov_b64_e32 v[104:105], 0
	v_mov_b64_e32 v[106:107], 0
	v_mov_b64_e32 v[108:109], 0
	v_mov_b64_e32 v[110:111], 0
	v_mov_b64_e32 v[112:113], 0
	v_mov_b64_e32 v[114:115], 0
	v_mov_b64_e32 v[116:117], 0
	v_mov_b64_e32 v[118:119], 0
	v_mov_b64_e32 v[120:121], 0
	v_mov_b64_e32 v[122:123], 0
	v_mov_b64_e32 v[124:125], 0
	v_mov_b64_e32 v[126:127], 0
	v_mov_b64_e32 v[128:129], 0

; template <class Epi, class Sched, bool ALIGN_EPI = false, bool SP2 = false>
; __device__ __forceinline__ void gemm_phase(PG8_LAS unsigned char* lds, const Gemm g, const Sched& S, const Epi& E, const int wid) {
;     ...
;         const bool has_next = S.next(ui + 1, nxt);
;         const char* nA = has_next ? (const char*)g.A + (size_t)nxt.pm * tstep : cA; const char* nB = has_next ? (const char*)g.Bt + (size_t)nxt.pn * tstep : cB;
;     ...
;         for (int a = 0; a < 2; ++a)
; #pragma unroll
;             for (int b = 0; b < 2; ++b)
; #pragma unroll
;                 for (int m = 0; m < 4; ++m)
; #pragma unroll
;                     for (int n = 0; n < 2; ++n) acc[a][b][m][n] = (f32x4){zf_, zf_, zf_, zf_};
.LBB0_428:
	s_ashr_i32 s21, s20, 31
	s_lshl_b64 s[26:27], s[20:21], 17
	s_add_u32 s26, s84, s26
	s_addc_u32 s27, s85, s27
	s_and_b64 s[28:29], s[6:7], exec
	s_cselect_b32 s21, s27, s25
	s_cselect_b32 s94, s26, s24
	s_ashr_i32 s19, s18, 31
	s_lshl_b64 s[28:29], s[18:19], 17
	s_add_u32 s28, s46, s28
	s_addc_u32 s29, s47, s29
	s_and_b64 s[30:31], s[6:7], exec
	s_cselect_b32 s19, s29, s23
	s_cselect_b32 s95, s28, s22
	s_mov_b32 s36, 0
	s_mov_b64 s[30:31], -1
	s_mov_b64 s[34:35], 0
	v_mov_b64_e32 v[2:3], 0
	v_mov_b64_e32 v[4:5], 0
	v_mov_b64_e32 v[6:7], 0
	v_mov_b64_e32 v[8:9], 0
	v_mov_b64_e32 v[10:11], 0
	v_mov_b64_e32 v[12:13], 0
	v_mov_b64_e32 v[14:15], 0
	v_mov_b64_e32 v[16:17], 0
	v_mov_b64_e32 v[18:19], 0
	v_mov_b64_e32 v[20:21], 0
	v_mov_b64_e32 v[22:23], 0
	v_mov_b64_e32 v[24:25], 0
	v_mov_b64_e32 v[26:27], 0
	v_mov_b64_e32 v[28:29], 0
	v_mov_b64_e32 v[30:31], 0
	v_mov_b64_e32 v[32:33], 0
	v_mov_b64_e32 v[34:35], 0
	v_mov_b64_e32 v[36:37], 0
	v_mov_b64_e32 v[38:39], 0
	v_mov_b64_e32 v[40:41], 0
	v_mov_b64_e32 v[42:43], 0
	v_mov_b64_e32 v[44:45], 0
	v_mov_b64_e32 v[46:47], 0
	v_mov_b64_e32 v[48:49], 0
	v_mov_b64_e32 v[50:51], 0
	v_mov_b64_e32 v[52:53], 0
	v_mov_b64_e32 v[54:55], 0
	v_mov_b64_e32 v[56:57], 0
	v_mov_b64_e32 v[58:59], 0
	v_mov_b64_e32 v[60:61], 0
	v_mov_b64_e32 v[62:63], 0
	v_mov_b64_e32 v[64:65], 0
	v_mov_b64_e32 v[66:67], 0
	v_mov_b64_e32 v[68:69], 0
	v_mov_b64_e32 v[70:71], 0
	v_mov_b64_e32 v[72:73], 0
	v_mov_b64_e32 v[74:75], 0
	v_mov_b64_e32 v[76:77], 0
	v_mov_b64_e32 v[78:79], 0
	v_mov_b64_e32 v[80:81], 0
	v_mov_b64_e32 v[82:83], 0
	v_mov_b64_e32 v[84:85], 0
	v_mov_b64_e32 v[86:87], 0
	v_mov_b64_e32 v[88:89], 0
	v_mov_b64_e32 v[90:91], 0
	v_mov_b64_e32 v[92:93], 0
	v_mov_b64_e32 v[94:95], 0
	v_mov_b64_e32 v[96:97], 0
	v_mov_b64_e32 v[98:99], 0
	v_mov_b64_e32 v[100:101], 0
	v_mov_b64_e32 v[102:103], 0
	v_mov_b64_e32 v[104:105], 0
	v_mov_b64_e32 v[106:107], 0
	v_mov_b64_e32 v[108:109], 0
	v_mov_b64_e32 v[110:111], 0
	v_mov_b64_e32 v[112:113], 0
	v_mov_b64_e32 v[114:115], 0
	v_mov_b64_e32 v[116:117], 0
	v_mov_b64_e32 v[118:119], 0
	v_mov_b64_e32 v[120:121], 0
	v_mov_b64_e32 v[122:123], 0
	v_mov_b64_e32 v[124:125], 0
	v_mov_b64_e32 v[126:127], 0
	v_mov_b64_e32 v[128:129], 0

; template <class Epi, class Sched, bool ALIGN_EPI = false, bool SP2 = false>
; __device__ __forceinline__ void gemm_phase(PG8_LAS unsigned char* lds, const Gemm g, const Sched& S, const Epi& E, const int wid) {
;     ...
;         const bool has_next = S.next(ui + 1, nxt);
;         const char* nA = has_next ? (const char*)g.A + (size_t)nxt.pm * tstep : cA; const char* nB = has_next ? (const char*)g.Bt + (size_t)nxt.pn * tstep : cB;
;     ...
;         for (int a = 0; a < 2; ++a)
; #pragma unroll
;             for (int b = 0; b < 2; ++b)
; #pragma unroll
;                 for (int m = 0; m < 4; ++m)
; #pragma unroll
;                     for (int n = 0; n < 2; ++n) acc[a][b][m][n] = (f32x4){zf_, zf_, zf_, zf_};
.LBB0_452:
	s_ashr_i32 s19, s18, 31
	s_lshl_b64 s[24:25], s[18:19], 17
	s_add_u32 s24, s46, s24
	s_addc_u32 s25, s47, s25
	s_and_b64 s[26:27], s[6:7], exec
	s_cselect_b32 s19, s25, s23
	s_cselect_b32 s68, s24, s22
	s_ashr_i32 s17, s16, 31
	s_lshl_b64 s[26:27], s[16:17], 17
	s_add_u32 s26, s84, s26
	s_addc_u32 s27, s85, s27
	s_and_b64 s[28:29], s[6:7], exec
	s_cselect_b32 s17, s27, s21
	s_cselect_b32 s90, s26, s20
	s_mov_b32 s34, 0
	s_mov_b64 s[28:29], -1
	s_mov_b64 s[30:31], 0
	v_mov_b64_e32 v[2:3], 0
	v_mov_b64_e32 v[4:5], 0
	v_mov_b64_e32 v[6:7], 0
	v_mov_b64_e32 v[8:9], 0
	v_mov_b64_e32 v[10:11], 0
	v_mov_b64_e32 v[12:13], 0
	v_mov_b64_e32 v[14:15], 0
	v_mov_b64_e32 v[16:17], 0
	v_mov_b64_e32 v[18:19], 0
	v_mov_b64_e32 v[20:21], 0
	v_mov_b64_e32 v[22:23], 0
	v_mov_b64_e32 v[24:25], 0
	v_mov_b64_e32 v[26:27], 0
	v_mov_b64_e32 v[28:29], 0
	v_mov_b64_e32 v[30:31], 0
	v_mov_b64_e32 v[32:33], 0
	v_mov_b64_e32 v[34:35], 0
	v_mov_b64_e32 v[36:37], 0
	v_mov_b64_e32 v[38:39], 0
	v_mov_b64_e32 v[40:41], 0
	v_mov_b64_e32 v[42:43], 0
	v_mov_b64_e32 v[44:45], 0
	v_mov_b64_e32 v[46:47], 0
	v_mov_b64_e32 v[48:49], 0
	v_mov_b64_e32 v[50:51], 0
	v_mov_b64_e32 v[52:53], 0
	v_mov_b64_e32 v[54:55], 0
	v_mov_b64_e32 v[56:57], 0
	v_mov_b64_e32 v[58:59], 0
	v_mov_b64_e32 v[60:61], 0
	v_mov_b64_e32 v[62:63], 0
	v_mov_b64_e32 v[64:65], 0
	v_mov_b64_e32 v[66:67], 0
	v_mov_b64_e32 v[68:69], 0
	v_mov_b64_e32 v[70:71], 0
	v_mov_b64_e32 v[72:73], 0
	v_mov_b64_e32 v[74:75], 0
	v_mov_b64_e32 v[76:77], 0
	v_mov_b64_e32 v[78:79], 0
	v_mov_b64_e32 v[80:81], 0
	v_mov_b64_e32 v[82:83], 0
	v_mov_b64_e32 v[84:85], 0
	v_mov_b64_e32 v[86:87], 0
	v_mov_b64_e32 v[88:89], 0
	v_mov_b64_e32 v[90:91], 0
	v_mov_b64_e32 v[92:93], 0
	v_mov_b64_e32 v[94:95], 0
	v_mov_b64_e32 v[96:97], 0
	v_mov_b64_e32 v[98:99], 0
	v_mov_b64_e32 v[100:101], 0
	v_mov_b64_e32 v[102:103], 0
	v_mov_b64_e32 v[104:105], 0
	v_mov_b64_e32 v[106:107], 0
	v_mov_b64_e32 v[108:109], 0
	v_mov_b64_e32 v[110:111], 0
	v_mov_b64_e32 v[112:113], 0
	v_mov_b64_e32 v[114:115], 0
	v_mov_b64_e32 v[116:117], 0
	v_mov_b64_e32 v[118:119], 0
	v_mov_b64_e32 v[120:121], 0
	v_mov_b64_e32 v[122:123], 0
	v_mov_b64_e32 v[124:125], 0
	v_mov_b64_e32 v[126:127], 0
	v_mov_b64_e32 v[128:129], 0

; template <class Epi, class Sched, bool ALIGN_EPI = false, bool SP2 = false>
; __device__ __forceinline__ void gemm_phase(PG8_LAS unsigned char* lds, const Gemm g, const Sched& S, const Epi& E, const int wid) {
;     ...
;         const bool has_next = S.next(ui + 1, nxt);
;         const char* nA = has_next ? (const char*)g.A + (size_t)nxt.pm * tstep : cA; const char* nB = has_next ? (const char*)g.Bt + (size_t)nxt.pn * tstep : cB;
;     ...
;         for (int a = 0; a < 2; ++a)
; #pragma unroll
;             for (int b = 0; b < 2; ++b)
; #pragma unroll
;                 for (int m = 0; m < 4; ++m)
; #pragma unroll
;                     for (int n = 0; n < 2; ++n) acc[a][b][m][n] = (f32x4){zf_, zf_, zf_, zf_};
.LBB0_477:
	s_ashr_i32 s25, s24, 31
	s_lshl_b64 s[26:27], s[24:25], 20
	s_add_u32 s26, s45, s26
	s_addc_u32 s27, s52, s27
	s_and_b64 s[28:29], s[6:7], exec
	s_cselect_b32 s25, s27, s35
	s_cselect_b32 s31, s26, s34
	s_ashr_i32 s23, s22, 31
	s_lshl_b64 s[28:29], s[22:23], 20
	s_add_u32 s28, s85, s28
	s_addc_u32 s29, s91, s29
	s_and_b64 s[38:39], s[6:7], exec
	s_cselect_b32 s23, s29, s37
	s_cselect_b32 s46, s28, s36
	s_add_u32 s34, s34, 0x80080
	s_addc_u32 s35, s35, 0
	s_add_u32 s47, s36, 0x100
	s_addc_u32 s50, s37, 0
	s_mov_b32 s55, -2
	v_mov_b64_e32 v[2:3], 0
	v_mov_b64_e32 v[4:5], 0
	v_mov_b64_e32 v[6:7], 0
	v_mov_b64_e32 v[8:9], 0
	v_mov_b64_e32 v[10:11], 0
	v_mov_b64_e32 v[12:13], 0
	v_mov_b64_e32 v[14:15], 0
	v_mov_b64_e32 v[16:17], 0
	v_mov_b64_e32 v[18:19], 0
	v_mov_b64_e32 v[20:21], 0
	v_mov_b64_e32 v[22:23], 0
	v_mov_b64_e32 v[24:25], 0
	v_mov_b64_e32 v[26:27], 0
	v_mov_b64_e32 v[28:29], 0
	v_mov_b64_e32 v[30:31], 0
	v_mov_b64_e32 v[32:33], 0
	v_mov_b64_e32 v[34:35], 0
	v_mov_b64_e32 v[36:37], 0
	v_mov_b64_e32 v[38:39], 0
	v_mov_b64_e32 v[40:41], 0
	v_mov_b64_e32 v[42:43], 0
	v_mov_b64_e32 v[44:45], 0
	v_mov_b64_e32 v[46:47], 0
	v_mov_b64_e32 v[48:49], 0
	v_mov_b64_e32 v[50:51], 0
	v_mov_b64_e32 v[52:53], 0
	v_mov_b64_e32 v[54:55], 0
	v_mov_b64_e32 v[56:57], 0
	v_mov_b64_e32 v[58:59], 0
	v_mov_b64_e32 v[60:61], 0
	v_mov_b64_e32 v[62:63], 0
	v_mov_b64_e32 v[64:65], 0
	v_mov_b64_e32 v[66:67], 0
	v_mov_b64_e32 v[68:69], 0
	v_mov_b64_e32 v[70:71], 0
	v_mov_b64_e32 v[72:73], 0
	v_mov_b64_e32 v[74:75], 0
	v_mov_b64_e32 v[76:77], 0
	v_mov_b64_e32 v[78:79], 0
	v_mov_b64_e32 v[80:81], 0
	v_mov_b64_e32 v[82:83], 0
	v_mov_b64_e32 v[84:85], 0
	v_mov_b64_e32 v[86:87], 0
	v_mov_b64_e32 v[88:89], 0
	v_mov_b64_e32 v[90:91], 0
	v_mov_b64_e32 v[92:93], 0
	v_mov_b64_e32 v[94:95], 0
	v_mov_b64_e32 v[96:97], 0
	v_mov_b64_e32 v[98:99], 0
	v_mov_b64_e32 v[100:101], 0
	v_mov_b64_e32 v[102:103], 0
	v_mov_b64_e32 v[104:105], 0
	v_mov_b64_e32 v[106:107], 0
	v_mov_b64_e32 v[108:109], 0
	v_mov_b64_e32 v[110:111], 0
	v_mov_b64_e32 v[112:113], 0
	v_mov_b64_e32 v[114:115], 0
	v_mov_b64_e32 v[116:117], 0
	v_mov_b64_e32 v[118:119], 0
	v_mov_b64_e32 v[120:121], 0
	v_mov_b64_e32 v[122:123], 0
	v_mov_b64_e32 v[124:125], 0
	v_mov_b64_e32 v[126:127], 0
	v_mov_b64_e32 v[128:129], 0

; template <class Epi, class Sched, bool ALIGN_EPI = false, bool SP2 = false>
; __device__ __forceinline__ void gemm_phase(PG8_LAS unsigned char* lds, const Gemm g, const Sched& S, const Epi& E, const int wid) {
;     ...
;         const bool has_next = S.next(ui + 1, nxt);
;         const char* nA = has_next ? (const char*)g.A + (size_t)nxt.pm * tstep : cA; const char* nB = has_next ? (const char*)g.Bt + (size_t)nxt.pn * tstep : cB;
;     ...
;         for (int a = 0; a < 2; ++a)
; #pragma unroll
;             for (int b = 0; b < 2; ++b)
; #pragma unroll
;                 for (int m = 0; m < 4; ++m)
; #pragma unroll
;                     for (int n = 0; n < 2; ++n) acc[a][b][m][n] = (f32x4){zf_, zf_, zf_, zf_};
.LBB0_499:
	s_ashr_i32 s25, s24, 31
	s_lshl_b64 s[26:27], s[24:25], 20
	s_add_u32 s26, s45, s26
	s_addc_u32 s27, s52, s27
	s_and_b64 s[28:29], s[6:7], exec
	s_cselect_b32 s25, s27, s35
	s_cselect_b32 s31, s26, s34
	s_ashr_i32 s23, s22, 31
	s_lshl_b64 s[28:29], s[22:23], 20
	s_add_u32 s28, s84, s28
	s_addc_u32 s29, s85, s29
	s_and_b64 s[38:39], s[6:7], exec
	s_cselect_b32 s23, s29, s37
	s_cselect_b32 s46, s28, s36
	s_add_u32 s34, s34, 0x80080
	s_addc_u32 s35, s35, 0
	s_add_u32 s47, s36, 0x100
	s_addc_u32 s50, s37, 0
	s_mov_b32 s55, -2
	v_mov_b64_e32 v[2:3], 0
	v_mov_b64_e32 v[4:5], 0
	v_mov_b64_e32 v[6:7], 0
	v_mov_b64_e32 v[8:9], 0
	v_mov_b64_e32 v[10:11], 0
	v_mov_b64_e32 v[12:13], 0
	v_mov_b64_e32 v[14:15], 0
	v_mov_b64_e32 v[16:17], 0
	v_mov_b64_e32 v[18:19], 0
	v_mov_b64_e32 v[20:21], 0
	v_mov_b64_e32 v[22:23], 0
	v_mov_b64_e32 v[24:25], 0
	v_mov_b64_e32 v[26:27], 0
	v_mov_b64_e32 v[28:29], 0
	v_mov_b64_e32 v[30:31], 0
	v_mov_b64_e32 v[32:33], 0
	v_mov_b64_e32 v[34:35], 0
	v_mov_b64_e32 v[36:37], 0
	v_mov_b64_e32 v[38:39], 0
	v_mov_b64_e32 v[40:41], 0
	v_mov_b64_e32 v[42:43], 0
	v_mov_b64_e32 v[44:45], 0
	v_mov_b64_e32 v[46:47], 0
	v_mov_b64_e32 v[48:49], 0
	v_mov_b64_e32 v[50:51], 0
	v_mov_b64_e32 v[52:53], 0
	v_mov_b64_e32 v[54:55], 0
	v_mov_b64_e32 v[56:57], 0
	v_mov_b64_e32 v[58:59], 0
	v_mov_b64_e32 v[60:61], 0
	v_mov_b64_e32 v[62:63], 0
	v_mov_b64_e32 v[64:65], 0
	v_mov_b64_e32 v[66:67], 0
	v_mov_b64_e32 v[68:69], 0
	v_mov_b64_e32 v[70:71], 0
	v_mov_b64_e32 v[72:73], 0
	v_mov_b64_e32 v[74:75], 0
	v_mov_b64_e32 v[76:77], 0
	v_mov_b64_e32 v[78:79], 0
	v_mov_b64_e32 v[80:81], 0
	v_mov_b64_e32 v[82:83], 0
	v_mov_b64_e32 v[84:85], 0
	v_mov_b64_e32 v[86:87], 0
	v_mov_b64_e32 v[88:89], 0
	v_mov_b64_e32 v[90:91], 0
	v_mov_b64_e32 v[92:93], 0
	v_mov_b64_e32 v[94:95], 0
	v_mov_b64_e32 v[96:97], 0
	v_mov_b64_e32 v[98:99], 0
	v_mov_b64_e32 v[100:101], 0
	v_mov_b64_e32 v[102:103], 0
	v_mov_b64_e32 v[104:105], 0
	v_mov_b64_e32 v[106:107], 0
	v_mov_b64_e32 v[108:109], 0
	v_mov_b64_e32 v[110:111], 0
	v_mov_b64_e32 v[112:113], 0
	v_mov_b64_e32 v[114:115], 0
	v_mov_b64_e32 v[116:117], 0
	v_mov_b64_e32 v[118:119], 0
	v_mov_b64_e32 v[120:121], 0
	v_mov_b64_e32 v[122:123], 0
	v_mov_b64_e32 v[124:125], 0
	v_mov_b64_e32 v[126:127], 0
	v_mov_b64_e32 v[128:129], 0

; template <class Epi, class Sched, bool ALIGN_EPI = false, bool SP2 = false>
; __device__ __forceinline__ void gemm_phase(PG8_LAS unsigned char* lds, const Gemm g, const Sched& S, const Epi& E, const int wid) {
;     ...
;         const bool has_next = S.next(ui + 1, nxt);
;         const char* nA = has_next ? (const char*)g.A + (size_t)nxt.pm * tstep : cA; const char* nB = has_next ? (const char*)g.Bt + (size_t)nxt.pn * tstep : cB;
;     ...
;         for (int a = 0; a < 2; ++a)
; #pragma unroll
;             for (int b = 0; b < 2; ++b)
; #pragma unroll
;                 for (int m = 0; m < 4; ++m)
; #pragma unroll
;                     for (int n = 0; n < 2; ++n) acc[a][b][m][n] = (f32x4){zf_, zf_, zf_, zf_};
.LBB0_529:
	s_ashr_i32 s21, s20, 31
	s_lshl_b64 s[22:23], s[20:21], 20
	s_add_u32 s22, s36, s22
	s_addc_u32 s23, s37, s23
	s_and_b64 s[24:25], s[6:7], exec
	s_cselect_b32 s21, s23, s29
	s_cselect_b32 s66, s22, s28
	s_ashr_i32 s19, s18, 31
	s_lshl_b64 s[24:25], s[18:19], 20
	s_add_u32 s24, s45, s24
	s_addc_u32 s25, s52, s25
	s_and_b64 s[34:35], s[6:7], exec
	s_cselect_b32 s19, s25, s31
	s_cselect_b32 s67, s24, s30
	s_add_u32 s28, s28, 0x80080
	s_addc_u32 s29, s29, 0
	s_add_u32 s68, s30, 0x100
	s_addc_u32 s84, s31, 0
	s_mov_b32 s85, -2
	v_mov_b64_e32 v[2:3], 0
	v_mov_b64_e32 v[4:5], 0
	v_mov_b64_e32 v[6:7], 0
	v_mov_b64_e32 v[8:9], 0
	v_mov_b64_e32 v[10:11], 0
	v_mov_b64_e32 v[12:13], 0
	v_mov_b64_e32 v[14:15], 0
	v_mov_b64_e32 v[16:17], 0
	v_mov_b64_e32 v[18:19], 0
	v_mov_b64_e32 v[20:21], 0
	v_mov_b64_e32 v[22:23], 0
	v_mov_b64_e32 v[24:25], 0
	v_mov_b64_e32 v[26:27], 0
	v_mov_b64_e32 v[28:29], 0
	v_mov_b64_e32 v[30:31], 0
	v_mov_b64_e32 v[32:33], 0
	v_mov_b64_e32 v[34:35], 0
	v_mov_b64_e32 v[36:37], 0
	v_mov_b64_e32 v[38:39], 0
	v_mov_b64_e32 v[40:41], 0
	v_mov_b64_e32 v[42:43], 0
	v_mov_b64_e32 v[44:45], 0
	v_mov_b64_e32 v[46:47], 0
	v_mov_b64_e32 v[48:49], 0
	v_mov_b64_e32 v[50:51], 0
	v_mov_b64_e32 v[52:53], 0
	v_mov_b64_e32 v[54:55], 0
	v_mov_b64_e32 v[56:57], 0
	v_mov_b64_e32 v[58:59], 0
	v_mov_b64_e32 v[60:61], 0
	v_mov_b64_e32 v[62:63], 0
	v_mov_b64_e32 v[64:65], 0
	v_mov_b64_e32 v[66:67], 0
	v_mov_b64_e32 v[68:69], 0
	v_mov_b64_e32 v[70:71], 0
	v_mov_b64_e32 v[72:73], 0
	v_mov_b64_e32 v[74:75], 0
	v_mov_b64_e32 v[76:77], 0
	v_mov_b64_e32 v[78:79], 0
	v_mov_b64_e32 v[80:81], 0
	v_mov_b64_e32 v[82:83], 0
	v_mov_b64_e32 v[84:85], 0
	v_mov_b64_e32 v[86:87], 0
	v_mov_b64_e32 v[88:89], 0
	v_mov_b64_e32 v[90:91], 0
	v_mov_b64_e32 v[92:93], 0
	v_mov_b64_e32 v[94:95], 0
	v_mov_b64_e32 v[96:97], 0
	v_mov_b64_e32 v[98:99], 0
	v_mov_b64_e32 v[100:101], 0
	v_mov_b64_e32 v[102:103], 0
	v_mov_b64_e32 v[104:105], 0
	v_mov_b64_e32 v[106:107], 0
	v_mov_b64_e32 v[108:109], 0
	v_mov_b64_e32 v[110:111], 0
	v_mov_b64_e32 v[112:113], 0
	v_mov_b64_e32 v[114:115], 0
	v_mov_b64_e32 v[116:117], 0
	v_mov_b64_e32 v[118:119], 0
	v_mov_b64_e32 v[120:121], 0
	v_mov_b64_e32 v[122:123], 0
	v_mov_b64_e32 v[124:125], 0
	v_mov_b64_e32 v[126:127], 0
	v_mov_b64_e32 v[128:129], 0

; template <class Epi, class Sched, bool ALIGN_EPI = false, bool SP2 = false>
; __device__ __forceinline__ void gemm_phase(PG8_LAS unsigned char* lds, const Gemm g, const Sched& S, const Epi& E, const int wid) {
;     ...
;         const bool has_next = S.next(ui + 1, nxt);
;         const char* nA = has_next ? (const char*)g.A + (size_t)nxt.pm * tstep : cA; const char* nB = has_next ? (const char*)g.Bt + (size_t)nxt.pn * tstep : cB;
;     ...
;         for (int a = 0; a < 2; ++a)
; #pragma unroll
;             for (int b = 0; b < 2; ++b)
; #pragma unroll
;                 for (int m = 0; m < 4; ++m)
; #pragma unroll
;                     for (int n = 0; n < 2; ++n) acc[a][b][m][n] = (f32x4){zf_, zf_, zf_, zf_};
.LBB0_551:
	s_ashr_i32 s21, s20, 31
	s_lshl_b64 s[22:23], s[20:21], 20
	s_add_u32 s22, s3, s22
	s_addc_u32 s23, s36, s23
	s_and_b64 s[24:25], s[6:7], exec
	s_cselect_b32 s21, s23, s29
	s_cselect_b32 s66, s22, s28
	s_ashr_i32 s19, s18, 31
	s_lshl_b64 s[24:25], s[18:19], 20
	s_add_u32 s24, s45, s24
	s_addc_u32 s25, s52, s25
	s_and_b64 s[34:35], s[6:7], exec
	s_cselect_b32 s19, s25, s31
	s_cselect_b32 s67, s24, s30
	s_add_u32 s28, s28, 0x80080
	s_addc_u32 s29, s29, 0
	s_add_u32 s68, s30, 0x100
	s_addc_u32 s84, s31, 0
	s_mov_b32 s85, -2
	v_mov_b64_e32 v[2:3], 0
	v_mov_b64_e32 v[4:5], 0
	v_mov_b64_e32 v[6:7], 0
	v_mov_b64_e32 v[8:9], 0
	v_mov_b64_e32 v[10:11], 0
	v_mov_b64_e32 v[12:13], 0
	v_mov_b64_e32 v[14:15], 0
	v_mov_b64_e32 v[16:17], 0
	v_mov_b64_e32 v[18:19], 0
	v_mov_b64_e32 v[20:21], 0
	v_mov_b64_e32 v[22:23], 0
	v_mov_b64_e32 v[24:25], 0
	v_mov_b64_e32 v[26:27], 0
	v_mov_b64_e32 v[28:29], 0
	v_mov_b64_e32 v[30:31], 0
	v_mov_b64_e32 v[32:33], 0
	v_mov_b64_e32 v[34:35], 0
	v_mov_b64_e32 v[36:37], 0
	v_mov_b64_e32 v[38:39], 0
	v_mov_b64_e32 v[40:41], 0
	v_mov_b64_e32 v[42:43], 0
	v_mov_b64_e32 v[44:45], 0
	v_mov_b64_e32 v[46:47], 0
	v_mov_b64_e32 v[48:49], 0
	v_mov_b64_e32 v[50:51], 0
	v_mov_b64_e32 v[52:53], 0
	v_mov_b64_e32 v[54:55], 0
	v_mov_b64_e32 v[56:57], 0
	v_mov_b64_e32 v[58:59], 0
	v_mov_b64_e32 v[60:61], 0
	v_mov_b64_e32 v[62:63], 0
	v_mov_b64_e32 v[64:65], 0
	v_mov_b64_e32 v[66:67], 0
	v_mov_b64_e32 v[68:69], 0
	v_mov_b64_e32 v[70:71], 0
	v_mov_b64_e32 v[72:73], 0
	v_mov_b64_e32 v[74:75], 0
	v_mov_b64_e32 v[76:77], 0
	v_mov_b64_e32 v[78:79], 0
	v_mov_b64_e32 v[80:81], 0
	v_mov_b64_e32 v[82:83], 0
	v_mov_b64_e32 v[84:85], 0
	v_mov_b64_e32 v[86:87], 0
	v_mov_b64_e32 v[88:89], 0
	v_mov_b64_e32 v[90:91], 0
	v_mov_b64_e32 v[92:93], 0
	v_mov_b64_e32 v[94:95], 0
	v_mov_b64_e32 v[96:97], 0
	v_mov_b64_e32 v[98:99], 0
	v_mov_b64_e32 v[100:101], 0
	v_mov_b64_e32 v[102:103], 0
	v_mov_b64_e32 v[104:105], 0
	v_mov_b64_e32 v[106:107], 0
	v_mov_b64_e32 v[108:109], 0
	v_mov_b64_e32 v[110:111], 0
	v_mov_b64_e32 v[112:113], 0
	v_mov_b64_e32 v[114:115], 0
	v_mov_b64_e32 v[116:117], 0
	v_mov_b64_e32 v[118:119], 0
	v_mov_b64_e32 v[120:121], 0
	v_mov_b64_e32 v[122:123], 0
	v_mov_b64_e32 v[124:125], 0
	v_mov_b64_e32 v[126:127], 0
	v_mov_b64_e32 v[128:129], 0

; template <class Epi, class Sched, bool ALIGN_EPI = false, bool SP2 = false>
; __device__ __forceinline__ void gemm_phase(PG8_LAS unsigned char* lds, const Gemm g, const Sched& S, const Epi& E, const int wid) {
;     ...
;         const bool has_next = S.next(ui + 1, nxt);
;         const char* nA = has_next ? (const char*)g.A + (size_t)nxt.pm * tstep : cA; const char* nB = has_next ? (const char*)g.Bt + (size_t)nxt.pn * tstep : cB;
;     ...
;         for (int a = 0; a < 2; ++a)
; #pragma unroll
;             for (int b = 0; b < 2; ++b)
; #pragma unroll
;                 for (int m = 0; m < 4; ++m)
; #pragma unroll
;                     for (int n = 0; n < 2; ++n) acc[a][b][m][n] = (f32x4){zf_, zf_, zf_, zf_};
.LBB0_633:
	s_ashr_i32 s23, s22, 31
	s_lshl_b64 s[24:25], s[22:23], 20
	s_add_u32 s24, s38, s24
	s_addc_u32 s25, s39, s25
	s_and_b64 s[26:27], s[6:7], exec
	s_cselect_b32 s19, s25, s31
	s_cselect_b32 s23, s24, s30
	s_ashr_i32 s21, s20, 31
	s_lshl_b64 s[26:27], s[20:21], 20
	s_add_u32 s26, s40, s26
	s_addc_u32 s27, s41, s27
	s_and_b64 s[36:37], s[6:7], exec
	s_cselect_b32 s21, s27, s35
	s_cselect_b32 s29, s26, s34
	s_add_u32 s30, s30, 0x80080
	s_addc_u32 s31, s31, 0
	s_add_u32 s46, s34, 0x100
	s_addc_u32 s47, s35, 0
	s_mov_b32 s50, -2
	v_mov_b64_e32 v[2:3], 0
	v_mov_b64_e32 v[4:5], 0
	v_mov_b64_e32 v[6:7], 0
	v_mov_b64_e32 v[8:9], 0
	v_mov_b64_e32 v[10:11], 0
	v_mov_b64_e32 v[12:13], 0
	v_mov_b64_e32 v[14:15], 0
	v_mov_b64_e32 v[16:17], 0
	v_mov_b64_e32 v[18:19], 0
	v_mov_b64_e32 v[20:21], 0
	v_mov_b64_e32 v[22:23], 0
	v_mov_b64_e32 v[24:25], 0
	v_mov_b64_e32 v[26:27], 0
	v_mov_b64_e32 v[28:29], 0
	v_mov_b64_e32 v[30:31], 0
	v_mov_b64_e32 v[32:33], 0
	v_mov_b64_e32 v[34:35], 0
	v_mov_b64_e32 v[36:37], 0
	v_mov_b64_e32 v[38:39], 0
	v_mov_b64_e32 v[40:41], 0
	v_mov_b64_e32 v[42:43], 0
	v_mov_b64_e32 v[44:45], 0
	v_mov_b64_e32 v[46:47], 0
	v_mov_b64_e32 v[48:49], 0
	v_mov_b64_e32 v[50:51], 0
	v_mov_b64_e32 v[52:53], 0
	v_mov_b64_e32 v[54:55], 0
	v_mov_b64_e32 v[56:57], 0
	v_mov_b64_e32 v[58:59], 0
	v_mov_b64_e32 v[60:61], 0
	v_mov_b64_e32 v[62:63], 0
	v_mov_b64_e32 v[64:65], 0
	v_mov_b64_e32 v[66:67], 0
	v_mov_b64_e32 v[68:69], 0
	v_mov_b64_e32 v[70:71], 0
	v_mov_b64_e32 v[72:73], 0
	v_mov_b64_e32 v[74:75], 0
	v_mov_b64_e32 v[76:77], 0
	v_mov_b64_e32 v[78:79], 0
	v_mov_b64_e32 v[80:81], 0
	v_mov_b64_e32 v[82:83], 0
	v_mov_b64_e32 v[84:85], 0
	v_mov_b64_e32 v[86:87], 0
	v_mov_b64_e32 v[88:89], 0
	v_mov_b64_e32 v[90:91], 0
	v_mov_b64_e32 v[92:93], 0
	v_mov_b64_e32 v[94:95], 0
	v_mov_b64_e32 v[96:97], 0
	v_mov_b64_e32 v[98:99], 0
	v_mov_b64_e32 v[100:101], 0
	v_mov_b64_e32 v[102:103], 0
	v_mov_b64_e32 v[104:105], 0
	v_mov_b64_e32 v[106:107], 0
	v_mov_b64_e32 v[108:109], 0
	v_mov_b64_e32 v[110:111], 0
	v_mov_b64_e32 v[112:113], 0
	v_mov_b64_e32 v[114:115], 0
	v_mov_b64_e32 v[116:117], 0
	v_mov_b64_e32 v[118:119], 0
	v_mov_b64_e32 v[120:121], 0
	v_mov_b64_e32 v[122:123], 0
	v_mov_b64_e32 v[124:125], 0
	v_mov_b64_e32 v[126:127], 0
	v_mov_b64_e32 v[128:129], 0
